# FFN1 epilogue pipeline: last quarter barrier moved behind the fourth quarter (drain stage = tile set-up only)
# speedup vs baseline: 1.0056x; 1.0029x over previous
; __device__ __forceinline__ float sigmoidf_(float x) { return __builtin_amdgcn_rcpf(1.0f + __expf(-x)); }
;     __device__ __forceinline__ void operator()(AccRef acc, const Unit& u, int wr, int wc, int fr, int fq) const {
;     ...
;                 float o[4][4];
; #pragma unroll
;                 for (int j = 0; j < 4; ++j) {
;                     const float v0 = acc[ai][0][0][n][j], v1 = acc[ai][0][1][n][j], v2 = acc[ai][0][2][n][j], v3 = acc[ai][0][3][n][j];
;                     const float g0 = acc[ai][1][0][n][j], g1 = acc[ai][1][1][n][j], g2 = acc[ai][1][2][n][j], g3 = acc[ai][1][3][n][j];
;                     const float pv3 = dpp_upd<0x111>(h3v[j], v3), pv2 = dpp_upd<0x111>(h2v[j], v2), pg3 = dpp_upd<0x111>(h3g[j], g3), pg2 = dpp_upd<0x111>(h2g[j], g2);
;                     const float hv0 = bvv[j] + w2v[j] * v0 + w1v[j] * pv3 + w0v[j] * pv2, hv1 = bvv[j] + w2v[j] * v1 + w1v[j] * v0 + w0v[j] * pv3;
;                     const float hv2 = bvv[j] + w2v[j] * v2 + w1v[j] * v1 + w0v[j] * v0, hv3 = bvv[j] + w2v[j] * v3 + w1v[j] * v2 + w0v[j] * v1;
;                     const float hg0 = bvg[j] + w2g[j] * g0 + w1g[j] * pg3 + w0g[j] * pg2, hg1 = bvg[j] + w2g[j] * g1 + w1g[j] * g0 + w0g[j] * pg3;
;                     const float hg2 = bvg[j] + w2g[j] * g2 + w1g[j] * g1 + w0g[j] * g0, hg3 = bvg[j] + w2g[j] * g3 + w1g[j] * g2 + w0g[j] * g1;
;                     o[0][j] = hg0 * sigmoidf_(hg0) * hv0; o[1][j] = hg1 * sigmoidf_(hg1) * hv1; o[2][j] = hg2 * sigmoidf_(hg2) * hv2; o[3][j] = hg3 * sigmoidf_(hg3) * hv3; }
; #pragma unroll
;                 for (int m = 0; m < 4; ++m) { u32x2 w; w.x = cvt_pk_bf16(o[m][0], o[m][1]); w.y = cvt_pk_bf16(o[m][2], o[m][3]);
;                     *(u32x2*)(Aout + (size_t)(row0 + ai * 128 + m) * FH + hc0 + 4 * n) = w; } } }
.LBB0_305:
	s_or_b64 exec, exec, s[34:35]
	s_waitcnt lgkmcnt(0)
	v_mov_b32_dpp v64, v8 row_shr:1 row_mask:0xf bank_mask:0xf
	v_mov_b32_dpp v65, v9 row_shr:1 row_mask:0xf bank_mask:0xf
	v_pk_fma_f32 v[44:45], v[24:25], v[120:121], v[124:125]
	v_mov_b32_dpp v40, v0 row_shr:1 row_mask:0xf bank_mask:0xf
	v_mov_b32_dpp v41, v1 row_shr:1 row_mask:0xf bank_mask:0xf
	v_pk_fma_f32 v[44:45], v[116:117], v[64:65], v[44:45]
	v_mov_b32_dpp v32, v20 row_shr:1 row_mask:0xf bank_mask:0xf
	v_pk_fma_f32 v[40:41], v[112:113], v[40:41], v[44:45]
	v_mov_b32_dpp v33, v21 row_shr:1 row_mask:0xf bank_mask:0xf
	v_exp_f32_e32 v44, v40
	v_exp_f32_e32 v45, v41
	v_pk_fma_f32 v[46:47], v[28:29], v[104:105], v[108:109]
	v_mov_b32_dpp v36, v12 row_shr:1 row_mask:0xf bank_mask:0xf
	v_pk_add_f32 v[44:45], v[44:45], 1.0 op_sel_hi:[1,0]
	v_rcp_f32_e32 v44, v44
	v_rcp_f32_e32 v45, v45
	v_mov_b32_dpp v37, v13 row_shr:1 row_mask:0xf bank_mask:0xf
	v_pk_fma_f32 v[46:47], v[100:101], v[32:33], v[46:47]
	v_mov_b32_dpp v66, v10 row_shr:1 row_mask:0xf bank_mask:0xf
	v_pk_fma_f32 v[36:37], v[96:97], v[36:37], v[46:47]
	v_pk_mul_f32 v[40:41], v[40:41], v[44:45]
	v_mov_b32_dpp v67, v11 row_shr:1 row_mask:0xf bank_mask:0xf
	v_pk_mul_f32 v[36:37], v[36:37], v[40:41]
	v_pk_fma_f32 v[40:41], v[26:27], v[122:123], v[126:127]
	v_mov_b32_dpp v42, v2 row_shr:1 row_mask:0xf bank_mask:0xf
	v_mov_b32_dpp v43, v3 row_shr:1 row_mask:0xf bank_mask:0xf
	v_pk_fma_f32 v[40:41], v[118:119], v[66:67], v[40:41]
	v_cvt_pk_bf16_f32 v146, v36, v37
	v_pk_fma_f32 v[40:41], v[114:115], v[42:43], v[40:41]
	v_mov_b32_dpp v34, v22 row_shr:1 row_mask:0xf bank_mask:0xf
	v_exp_f32_e32 v42, v40
	v_exp_f32_e32 v43, v41
	v_mov_b32_dpp v35, v23 row_shr:1 row_mask:0xf bank_mask:0xf
	v_pk_add_f32 v[42:43], v[42:43], 1.0 op_sel_hi:[1,0]
	v_rcp_f32_e32 v42, v42
	v_rcp_f32_e32 v43, v43
	v_pk_fma_f32 v[44:45], v[30:31], v[106:107], v[110:111]
	v_mov_b32_dpp v38, v14 row_shr:1 row_mask:0xf bank_mask:0xf
	v_mov_b32_dpp v39, v15 row_shr:1 row_mask:0xf bank_mask:0xf
	v_pk_fma_f32 v[44:45], v[102:103], v[34:35], v[44:45]
	v_pk_mul_f32 v[40:41], v[40:41], v[42:43]
	v_pk_fma_f32 v[38:39], v[98:99], v[38:39], v[44:45]
	v_pk_fma_f32 v[8:9], v[8:9], v[120:121], v[124:125]
	v_pk_mul_f32 v[38:39], v[38:39], v[40:41]
	v_pk_fma_f32 v[20:21], v[20:21], v[104:105], v[108:109]
	v_cvt_pk_bf16_f32 v147, v38, v39
	v_pk_fma_f32 v[38:39], v[4:5], v[120:121], v[124:125]
	global_store_dwordx4 v[132:133], v[144:147], off
	v_pk_fma_f32 v[38:39], v[24:25], v[116:117], v[38:39]
	s_and_b64 vcc, exec, s[12:13]
	v_pk_fma_f32 v[38:39], v[112:113], v[64:65], v[38:39]
	s_mov_b32 s35, s24
	v_exp_f32_e32 v36, v38
	v_exp_f32_e32 v37, v39
	s_mov_b32 s34, s26
	s_mov_b64 s[38:39], s[30:31]
	v_pk_add_f32 v[36:37], v[36:37], 1.0 op_sel_hi:[1,0]
	v_rcp_f32_e32 v36, v36
	v_rcp_f32_e32 v37, v37
	v_pk_fma_f32 v[40:41], v[16:17], v[104:105], v[108:109]
	s_mov_b64 s[36:37], s[28:29]
	v_pk_fma_f32 v[40:41], v[28:29], v[100:101], v[40:41]
	v_pk_mul_f32 v[36:37], v[38:39], v[36:37]
	v_pk_fma_f32 v[32:33], v[96:97], v[32:33], v[40:41]
	v_pk_fma_f32 v[40:41], v[18:19], v[106:107], v[110:111]
	v_pk_mul_f32 v[32:33], v[32:33], v[36:37]
	v_pk_fma_f32 v[36:37], v[6:7], v[122:123], v[126:127]
	v_cvt_pk_bf16_f32 v156, v32, v33
	v_pk_fma_f32 v[36:37], v[26:27], v[118:119], v[36:37]
	v_pk_fma_f32 v[40:41], v[30:31], v[102:103], v[40:41]
	v_pk_fma_f32 v[36:37], v[114:115], v[66:67], v[36:37]
	v_pk_fma_f32 v[34:35], v[98:99], v[34:35], v[40:41]
	v_exp_f32_e32 v38, v36
	v_exp_f32_e32 v39, v37
	s_nop 0
	v_pk_add_f32 v[38:39], v[38:39], 1.0 op_sel_hi:[1,0]
	v_rcp_f32_e32 v38, v38
	v_rcp_f32_e32 v39, v39
	s_nop 0
	v_pk_mul_f32 v[36:37], v[36:37], v[38:39]
	s_nop 0
	v_pk_mul_f32 v[34:35], v[34:35], v[36:37]
	s_nop 0
	v_cvt_pk_bf16_f32 v157, v34, v35
	v_pk_fma_f32 v[34:35], v[0:1], v[120:121], v[124:125]
	global_store_dwordx4 v[128:129], v[154:157], off
	v_pk_fma_f32 v[34:35], v[4:5], v[116:117], v[34:35]
	v_pk_fma_f32 v[0:1], v[0:1], v[116:117], v[8:9]
	v_pk_fma_f32 v[24:25], v[24:25], v[112:113], v[34:35]
	v_pk_fma_f32 v[0:1], v[4:5], v[112:113], v[0:1]
	v_exp_f32_e32 v32, v24
	v_exp_f32_e32 v33, v25
	v_exp_f32_e32 v8, v0
	v_pk_add_f32 v[32:33], v[32:33], 1.0 op_sel_hi:[1,0]
	v_rcp_f32_e32 v32, v32
	v_rcp_f32_e32 v33, v33
	v_pk_fma_f32 v[34:35], v[12:13], v[104:105], v[108:109]
	v_pk_fma_f32 v[4:5], v[10:11], v[122:123], v[126:127]
	v_pk_fma_f32 v[34:35], v[16:17], v[100:101], v[34:35]
	v_pk_mul_f32 v[24:25], v[24:25], v[32:33]
	v_pk_fma_f32 v[28:29], v[28:29], v[96:97], v[34:35]
	v_pk_mul_f32 v[24:25], v[28:29], v[24:25]
	v_pk_fma_f32 v[28:29], v[2:3], v[122:123], v[126:127]
	v_pk_fma_f32 v[2:3], v[2:3], v[118:119], v[4:5]
	v_pk_fma_f32 v[28:29], v[6:7], v[118:119], v[28:29]
	v_pk_fma_f32 v[2:3], v[6:7], v[114:115], v[2:3]
	v_pk_fma_f32 v[26:27], v[26:27], v[114:115], v[28:29]
	v_exp_f32_e32 v28, v26
	v_exp_f32_e32 v29, v27
	v_exp_f32_e32 v9, v1
	v_exp_f32_e32 v4, v2
	v_exp_f32_e32 v5, v3
	v_cvt_pk_bf16_f32 v200, v24, v25
	v_pk_add_f32 v[28:29], v[28:29], 1.0 op_sel_hi:[1,0]
	v_pk_add_f32 v[8:9], v[8:9], 1.0 op_sel_hi:[1,0]
	v_pk_add_f32 v[4:5], v[4:5], 1.0 op_sel_hi:[1,0]
	v_rcp_f32_e32 v28, v28
	v_rcp_f32_e32 v29, v29
	v_rcp_f32_e32 v8, v8
	v_rcp_f32_e32 v9, v9
	v_rcp_f32_e32 v4, v4
	v_rcp_f32_e32 v5, v5
	v_pk_fma_f32 v[32:33], v[14:15], v[106:107], v[110:111]
	v_pk_fma_f32 v[10:11], v[22:23], v[106:107], v[110:111]
	v_pk_fma_f32 v[32:33], v[18:19], v[102:103], v[32:33]
	v_pk_fma_f32 v[12:13], v[12:13], v[100:101], v[20:21]
	v_pk_fma_f32 v[6:7], v[14:15], v[102:103], v[10:11]
	v_pk_fma_f32 v[30:31], v[30:31], v[98:99], v[32:33]
	v_pk_mul_f32 v[26:27], v[26:27], v[28:29]
	v_pk_fma_f32 v[12:13], v[16:17], v[96:97], v[12:13]
	v_pk_mul_f32 v[0:1], v[0:1], v[8:9]
	v_pk_fma_f32 v[6:7], v[18:19], v[98:99], v[6:7]
	v_pk_mul_f32 v[2:3], v[2:3], v[4:5]
	v_pk_mul_f32 v[26:27], v[30:31], v[26:27]
	v_pk_mul_f32 v[0:1], v[12:13], v[0:1]
	v_pk_mul_f32 v[2:3], v[6:7], v[2:3]
	v_cvt_pk_bf16_f32 v201, v26, v27
	v_cvt_pk_bf16_f32 v150, v0, v1
	v_cvt_pk_bf16_f32 v151, v2, v3
	global_store_dwordx4 v[88:89], v[198:201], off
	global_store_dwordx4 v[82:83], v[148:151], off
	s_barrier
	s_cbranch_vccnz .LBB0_324

; __device__ __forceinline__ float sigmoidf_(float x) { return __builtin_amdgcn_rcpf(1.0f + __expf(-x)); }
;     __device__ __forceinline__ void operator()(AccRef acc, const Unit& u, int wr, int wc, int fr, int fq) const {
;     ...
;                 float o[4][4];
; #pragma unroll
;                 for (int j = 0; j < 4; ++j) {
;                     const float v0 = acc[ai][0][0][n][j], v1 = acc[ai][0][1][n][j], v2 = acc[ai][0][2][n][j], v3 = acc[ai][0][3][n][j];
;                     const float g0 = acc[ai][1][0][n][j], g1 = acc[ai][1][1][n][j], g2 = acc[ai][1][2][n][j], g3 = acc[ai][1][3][n][j];
;                     const float pv3 = dpp_upd<0x111>(h3v[j], v3), pv2 = dpp_upd<0x111>(h2v[j], v2), pg3 = dpp_upd<0x111>(h3g[j], g3), pg2 = dpp_upd<0x111>(h2g[j], g2);
;                     const float hv0 = bvv[j] + w2v[j] * v0 + w1v[j] * pv3 + w0v[j] * pv2, hv1 = bvv[j] + w2v[j] * v1 + w1v[j] * v0 + w0v[j] * pv3;
;                     const float hv2 = bvv[j] + w2v[j] * v2 + w1v[j] * v1 + w0v[j] * v0, hv3 = bvv[j] + w2v[j] * v3 + w1v[j] * v2 + w0v[j] * v1;
;                     const float hg0 = bvg[j] + w2g[j] * g0 + w1g[j] * pg3 + w0g[j] * pg2, hg1 = bvg[j] + w2g[j] * g1 + w1g[j] * g0 + w0g[j] * pg3;
;                     const float hg2 = bvg[j] + w2g[j] * g2 + w1g[j] * g1 + w0g[j] * g0, hg3 = bvg[j] + w2g[j] * g3 + w1g[j] * g2 + w0g[j] * g1;
;                     o[0][j] = hg0 * sigmoidf_(hg0) * hv0; o[1][j] = hg1 * sigmoidf_(hg1) * hv1; o[2][j] = hg2 * sigmoidf_(hg2) * hv2; o[3][j] = hg3 * sigmoidf_(hg3) * hv3; }
; #pragma unroll
;                 for (int m = 0; m < 4; ++m) { u32x2 w; w.x = cvt_pk_bf16(o[m][0], o[m][1]); w.y = cvt_pk_bf16(o[m][2], o[m][3]);
;                     *(u32x2*)(Aout + (size_t)(row0 + ai * 128 + m) * FH + hc0 + 4 * n) = w; } } }
.LBB0_754:
	s_or_b64 exec, exec, s[40:41]
	s_waitcnt lgkmcnt(0)
	v_mov_b32_dpp v64, v8 row_shr:1 row_mask:0xf bank_mask:0xf
	v_mov_b32_dpp v65, v9 row_shr:1 row_mask:0xf bank_mask:0xf
	v_pk_fma_f32 v[44:45], v[24:25], v[120:121], v[124:125]
	v_mov_b32_dpp v40, v0 row_shr:1 row_mask:0xf bank_mask:0xf
	v_mov_b32_dpp v41, v1 row_shr:1 row_mask:0xf bank_mask:0xf
	v_pk_fma_f32 v[44:45], v[116:117], v[64:65], v[44:45]
	v_mov_b32_dpp v32, v20 row_shr:1 row_mask:0xf bank_mask:0xf
	v_pk_fma_f32 v[40:41], v[112:113], v[40:41], v[44:45]
	v_mov_b32_dpp v33, v21 row_shr:1 row_mask:0xf bank_mask:0xf
	v_exp_f32_e32 v44, v40
	v_exp_f32_e32 v45, v41
	v_pk_fma_f32 v[46:47], v[28:29], v[104:105], v[108:109]
	v_mov_b32_dpp v36, v12 row_shr:1 row_mask:0xf bank_mask:0xf
	v_pk_add_f32 v[44:45], v[44:45], 1.0 op_sel_hi:[1,0]
	v_rcp_f32_e32 v44, v44
	v_rcp_f32_e32 v45, v45
	v_mov_b32_dpp v37, v13 row_shr:1 row_mask:0xf bank_mask:0xf
	v_pk_fma_f32 v[46:47], v[100:101], v[32:33], v[46:47]
	v_mov_b32_dpp v66, v10 row_shr:1 row_mask:0xf bank_mask:0xf
	v_pk_fma_f32 v[36:37], v[96:97], v[36:37], v[46:47]
	v_pk_mul_f32 v[40:41], v[40:41], v[44:45]
	v_mov_b32_dpp v67, v11 row_shr:1 row_mask:0xf bank_mask:0xf
	v_pk_mul_f32 v[36:37], v[36:37], v[40:41]
	v_pk_fma_f32 v[40:41], v[26:27], v[122:123], v[126:127]
	v_mov_b32_dpp v42, v2 row_shr:1 row_mask:0xf bank_mask:0xf
	v_mov_b32_dpp v43, v3 row_shr:1 row_mask:0xf bank_mask:0xf
	v_pk_fma_f32 v[40:41], v[118:119], v[66:67], v[40:41]
	v_cvt_pk_bf16_f32 v146, v36, v37
	v_pk_fma_f32 v[40:41], v[114:115], v[42:43], v[40:41]
	v_mov_b32_dpp v34, v22 row_shr:1 row_mask:0xf bank_mask:0xf
	v_exp_f32_e32 v42, v40
	v_exp_f32_e32 v43, v41
	v_mov_b32_dpp v35, v23 row_shr:1 row_mask:0xf bank_mask:0xf
	v_pk_add_f32 v[42:43], v[42:43], 1.0 op_sel_hi:[1,0]
	v_rcp_f32_e32 v42, v42
	v_rcp_f32_e32 v43, v43
	v_pk_fma_f32 v[44:45], v[30:31], v[106:107], v[110:111]
	v_mov_b32_dpp v38, v14 row_shr:1 row_mask:0xf bank_mask:0xf
	v_mov_b32_dpp v39, v15 row_shr:1 row_mask:0xf bank_mask:0xf
	v_pk_fma_f32 v[44:45], v[102:103], v[34:35], v[44:45]
	v_pk_mul_f32 v[40:41], v[40:41], v[42:43]
	v_pk_fma_f32 v[38:39], v[98:99], v[38:39], v[44:45]
	v_pk_fma_f32 v[8:9], v[8:9], v[120:121], v[124:125]
	v_pk_mul_f32 v[38:39], v[38:39], v[40:41]
	v_pk_fma_f32 v[20:21], v[20:21], v[104:105], v[108:109]
	v_cvt_pk_bf16_f32 v147, v38, v39
	v_pk_fma_f32 v[38:39], v[4:5], v[120:121], v[124:125]
	global_store_dwordx4 v[132:133], v[144:147], off
	v_pk_fma_f32 v[38:39], v[24:25], v[116:117], v[38:39]
	s_and_b64 vcc, exec, s[14:15]
	v_pk_fma_f32 v[38:39], v[112:113], v[64:65], v[38:39]
	s_mov_b32 s41, s30
	v_exp_f32_e32 v36, v38
	v_exp_f32_e32 v37, v39
	s_mov_b32 s40, s34
	s_mov_b64 s[44:45], s[38:39]
	v_pk_add_f32 v[36:37], v[36:37], 1.0 op_sel_hi:[1,0]
	v_rcp_f32_e32 v36, v36
	v_rcp_f32_e32 v37, v37
	v_pk_fma_f32 v[40:41], v[16:17], v[104:105], v[108:109]
	s_mov_b64 s[42:43], s[36:37]
	v_pk_fma_f32 v[40:41], v[28:29], v[100:101], v[40:41]
	v_pk_mul_f32 v[36:37], v[38:39], v[36:37]
	v_pk_fma_f32 v[32:33], v[96:97], v[32:33], v[40:41]
	v_pk_fma_f32 v[40:41], v[18:19], v[106:107], v[110:111]
	v_pk_mul_f32 v[32:33], v[32:33], v[36:37]
	v_pk_fma_f32 v[36:37], v[6:7], v[122:123], v[126:127]
	v_cvt_pk_bf16_f32 v156, v32, v33
	v_pk_fma_f32 v[36:37], v[26:27], v[118:119], v[36:37]
	v_pk_fma_f32 v[40:41], v[30:31], v[102:103], v[40:41]
	v_pk_fma_f32 v[36:37], v[114:115], v[66:67], v[36:37]
	v_pk_fma_f32 v[34:35], v[98:99], v[34:35], v[40:41]
	v_exp_f32_e32 v38, v36
	v_exp_f32_e32 v39, v37
	s_nop 0
	v_pk_add_f32 v[38:39], v[38:39], 1.0 op_sel_hi:[1,0]
	v_rcp_f32_e32 v38, v38
	v_rcp_f32_e32 v39, v39
	s_nop 0
	v_pk_mul_f32 v[36:37], v[36:37], v[38:39]
	s_nop 0
	v_pk_mul_f32 v[34:35], v[34:35], v[36:37]
	s_nop 0
	v_cvt_pk_bf16_f32 v157, v34, v35
	v_pk_fma_f32 v[34:35], v[0:1], v[120:121], v[124:125]
	global_store_dwordx4 v[128:129], v[154:157], off
	v_pk_fma_f32 v[34:35], v[4:5], v[116:117], v[34:35]
	v_pk_fma_f32 v[0:1], v[0:1], v[116:117], v[8:9]
	v_pk_fma_f32 v[24:25], v[24:25], v[112:113], v[34:35]
	v_pk_fma_f32 v[0:1], v[4:5], v[112:113], v[0:1]
	v_exp_f32_e32 v32, v24
	v_exp_f32_e32 v33, v25
	v_exp_f32_e32 v8, v0
	v_pk_add_f32 v[32:33], v[32:33], 1.0 op_sel_hi:[1,0]
	v_rcp_f32_e32 v32, v32
	v_rcp_f32_e32 v33, v33
	v_pk_fma_f32 v[34:35], v[12:13], v[104:105], v[108:109]
	v_pk_fma_f32 v[4:5], v[10:11], v[122:123], v[126:127]
	v_pk_fma_f32 v[34:35], v[16:17], v[100:101], v[34:35]
	v_pk_mul_f32 v[24:25], v[24:25], v[32:33]
	v_pk_fma_f32 v[28:29], v[28:29], v[96:97], v[34:35]
	v_pk_mul_f32 v[24:25], v[28:29], v[24:25]
	v_pk_fma_f32 v[28:29], v[2:3], v[122:123], v[126:127]
	v_pk_fma_f32 v[2:3], v[2:3], v[118:119], v[4:5]
	v_pk_fma_f32 v[28:29], v[6:7], v[118:119], v[28:29]
	v_pk_fma_f32 v[2:3], v[6:7], v[114:115], v[2:3]
	v_pk_fma_f32 v[26:27], v[26:27], v[114:115], v[28:29]
	v_exp_f32_e32 v28, v26
	v_exp_f32_e32 v29, v27
	v_exp_f32_e32 v9, v1
	v_exp_f32_e32 v4, v2
	v_exp_f32_e32 v5, v3
	v_cvt_pk_bf16_f32 v200, v24, v25
	v_pk_add_f32 v[28:29], v[28:29], 1.0 op_sel_hi:[1,0]
	v_pk_add_f32 v[8:9], v[8:9], 1.0 op_sel_hi:[1,0]
	v_pk_add_f32 v[4:5], v[4:5], 1.0 op_sel_hi:[1,0]
	v_rcp_f32_e32 v28, v28
	v_rcp_f32_e32 v29, v29
	v_rcp_f32_e32 v8, v8
	v_rcp_f32_e32 v9, v9
	v_rcp_f32_e32 v4, v4
	v_rcp_f32_e32 v5, v5
	v_pk_fma_f32 v[32:33], v[14:15], v[106:107], v[110:111]
	v_pk_fma_f32 v[10:11], v[22:23], v[106:107], v[110:111]
	v_pk_fma_f32 v[32:33], v[18:19], v[102:103], v[32:33]
	v_pk_fma_f32 v[12:13], v[12:13], v[100:101], v[20:21]
	v_pk_fma_f32 v[6:7], v[14:15], v[102:103], v[10:11]
	v_pk_fma_f32 v[30:31], v[30:31], v[98:99], v[32:33]
	v_pk_mul_f32 v[26:27], v[26:27], v[28:29]
	v_pk_fma_f32 v[12:13], v[16:17], v[96:97], v[12:13]
	v_pk_mul_f32 v[0:1], v[0:1], v[8:9]
	v_pk_fma_f32 v[6:7], v[18:19], v[98:99], v[6:7]
	v_pk_mul_f32 v[2:3], v[2:3], v[4:5]
	v_pk_mul_f32 v[26:27], v[30:31], v[26:27]
	v_pk_mul_f32 v[0:1], v[12:13], v[0:1]
	v_pk_mul_f32 v[2:3], v[6:7], v[2:3]
	v_cvt_pk_bf16_f32 v201, v26, v27
	v_cvt_pk_bf16_f32 v150, v0, v1
	v_cvt_pk_bf16_f32 v151, v2, v3
	global_store_dwordx4 v[88:89], v[198:201], off
	global_store_dwordx4 v[82:83], v[148:151], off
	s_barrier
	s_cbranch_vccnz .LBB0_773

; __device__ __forceinline__ float sigmoidf_(float x) { return __builtin_amdgcn_rcpf(1.0f + __expf(-x)); }
;     __device__ __forceinline__ void operator()(AccRef acc, const Unit& u, int wr, int wc, int fr, int fq) const {
;     ...
;                 float o[4][4];
; #pragma unroll
;                 for (int j = 0; j < 4; ++j) {
;                     const float v0 = acc[ai][0][0][n][j], v1 = acc[ai][0][1][n][j], v2 = acc[ai][0][2][n][j], v3 = acc[ai][0][3][n][j];
;                     const float g0 = acc[ai][1][0][n][j], g1 = acc[ai][1][1][n][j], g2 = acc[ai][1][2][n][j], g3 = acc[ai][1][3][n][j];
;                     const float pv3 = dpp_upd<0x111>(h3v[j], v3), pv2 = dpp_upd<0x111>(h2v[j], v2), pg3 = dpp_upd<0x111>(h3g[j], g3), pg2 = dpp_upd<0x111>(h2g[j], g2);
;                     const float hv0 = bvv[j] + w2v[j] * v0 + w1v[j] * pv3 + w0v[j] * pv2, hv1 = bvv[j] + w2v[j] * v1 + w1v[j] * v0 + w0v[j] * pv3;
;                     const float hv2 = bvv[j] + w2v[j] * v2 + w1v[j] * v1 + w0v[j] * v0, hv3 = bvv[j] + w2v[j] * v3 + w1v[j] * v2 + w0v[j] * v1;
;                     const float hg0 = bvg[j] + w2g[j] * g0 + w1g[j] * pg3 + w0g[j] * pg2, hg1 = bvg[j] + w2g[j] * g1 + w1g[j] * g0 + w0g[j] * pg3;
;                     const float hg2 = bvg[j] + w2g[j] * g2 + w1g[j] * g1 + w0g[j] * g0, hg3 = bvg[j] + w2g[j] * g3 + w1g[j] * g2 + w0g[j] * g1;
;                     o[0][j] = hg0 * sigmoidf_(hg0) * hv0; o[1][j] = hg1 * sigmoidf_(hg1) * hv1; o[2][j] = hg2 * sigmoidf_(hg2) * hv2; o[3][j] = hg3 * sigmoidf_(hg3) * hv3; }
; #pragma unroll
;                 for (int m = 0; m < 4; ++m) { u32x2 w; w.x = cvt_pk_bf16(o[m][0], o[m][1]); w.y = cvt_pk_bf16(o[m][2], o[m][3]);
;                     *(u32x2*)(Aout + (size_t)(row0 + ai * 128 + m) * FH + hc0 + 4 * n) = w; } } }
.LBB0_1355:
	s_or_b64 exec, exec, s[42:43]
	s_waitcnt lgkmcnt(0)
	v_mov_b32_dpp v64, v8 row_shr:1 row_mask:0xf bank_mask:0xf
	v_mov_b32_dpp v65, v9 row_shr:1 row_mask:0xf bank_mask:0xf
	v_pk_fma_f32 v[44:45], v[24:25], v[120:121], v[124:125]
	v_mov_b32_dpp v40, v0 row_shr:1 row_mask:0xf bank_mask:0xf
	v_mov_b32_dpp v41, v1 row_shr:1 row_mask:0xf bank_mask:0xf
	v_pk_fma_f32 v[44:45], v[116:117], v[64:65], v[44:45]
	v_mov_b32_dpp v32, v20 row_shr:1 row_mask:0xf bank_mask:0xf
	v_pk_fma_f32 v[40:41], v[112:113], v[40:41], v[44:45]
	v_mov_b32_dpp v33, v21 row_shr:1 row_mask:0xf bank_mask:0xf
	v_exp_f32_e32 v44, v40
	v_exp_f32_e32 v45, v41
	v_pk_fma_f32 v[46:47], v[28:29], v[104:105], v[108:109]
	v_mov_b32_dpp v36, v12 row_shr:1 row_mask:0xf bank_mask:0xf
	v_pk_add_f32 v[44:45], v[44:45], 1.0 op_sel_hi:[1,0]
	v_rcp_f32_e32 v44, v44
	v_rcp_f32_e32 v45, v45
	v_mov_b32_dpp v37, v13 row_shr:1 row_mask:0xf bank_mask:0xf
	v_pk_fma_f32 v[46:47], v[100:101], v[32:33], v[46:47]
	v_mov_b32_dpp v66, v10 row_shr:1 row_mask:0xf bank_mask:0xf
	v_pk_fma_f32 v[36:37], v[96:97], v[36:37], v[46:47]
	v_pk_mul_f32 v[40:41], v[40:41], v[44:45]
	v_mov_b32_dpp v67, v11 row_shr:1 row_mask:0xf bank_mask:0xf
	v_pk_mul_f32 v[36:37], v[36:37], v[40:41]
	v_pk_fma_f32 v[40:41], v[26:27], v[122:123], v[126:127]
	v_mov_b32_dpp v42, v2 row_shr:1 row_mask:0xf bank_mask:0xf
	v_mov_b32_dpp v43, v3 row_shr:1 row_mask:0xf bank_mask:0xf
	v_pk_fma_f32 v[40:41], v[118:119], v[66:67], v[40:41]
	v_cvt_pk_bf16_f32 v146, v36, v37
	v_pk_fma_f32 v[40:41], v[114:115], v[42:43], v[40:41]
	v_mov_b32_dpp v34, v22 row_shr:1 row_mask:0xf bank_mask:0xf
	v_exp_f32_e32 v42, v40
	v_exp_f32_e32 v43, v41
	v_mov_b32_dpp v35, v23 row_shr:1 row_mask:0xf bank_mask:0xf
	v_pk_add_f32 v[42:43], v[42:43], 1.0 op_sel_hi:[1,0]
	v_rcp_f32_e32 v42, v42
	v_rcp_f32_e32 v43, v43
	v_pk_fma_f32 v[44:45], v[30:31], v[106:107], v[110:111]
	v_mov_b32_dpp v38, v14 row_shr:1 row_mask:0xf bank_mask:0xf
	v_mov_b32_dpp v39, v15 row_shr:1 row_mask:0xf bank_mask:0xf
	v_pk_fma_f32 v[44:45], v[102:103], v[34:35], v[44:45]
	v_pk_mul_f32 v[40:41], v[40:41], v[42:43]
	v_pk_fma_f32 v[38:39], v[98:99], v[38:39], v[44:45]
	v_pk_fma_f32 v[8:9], v[8:9], v[120:121], v[124:125]
	v_pk_mul_f32 v[38:39], v[38:39], v[40:41]
	v_pk_fma_f32 v[20:21], v[20:21], v[104:105], v[108:109]
	v_cvt_pk_bf16_f32 v147, v38, v39
	v_pk_fma_f32 v[38:39], v[4:5], v[120:121], v[124:125]
	global_store_dwordx4 v[132:133], v[144:147], off
	v_pk_fma_f32 v[38:39], v[24:25], v[116:117], v[38:39]
	s_and_b64 vcc, exec, s[14:15]
	v_pk_fma_f32 v[38:39], v[112:113], v[64:65], v[38:39]
	s_mov_b32 s43, s34
	v_exp_f32_e32 v36, v38
	v_exp_f32_e32 v37, v39
	s_mov_b32 s42, s36
	s_mov_b64 s[46:47], s[40:41]
	v_pk_add_f32 v[36:37], v[36:37], 1.0 op_sel_hi:[1,0]
	v_rcp_f32_e32 v36, v36
	v_rcp_f32_e32 v37, v37
	v_pk_fma_f32 v[40:41], v[16:17], v[104:105], v[108:109]
	s_mov_b64 s[44:45], s[38:39]
	v_pk_fma_f32 v[40:41], v[28:29], v[100:101], v[40:41]
	v_pk_mul_f32 v[36:37], v[38:39], v[36:37]
	v_pk_fma_f32 v[32:33], v[96:97], v[32:33], v[40:41]
	v_pk_fma_f32 v[40:41], v[18:19], v[106:107], v[110:111]
	v_pk_mul_f32 v[32:33], v[32:33], v[36:37]
	v_pk_fma_f32 v[36:37], v[6:7], v[122:123], v[126:127]
	v_cvt_pk_bf16_f32 v156, v32, v33
	v_pk_fma_f32 v[36:37], v[26:27], v[118:119], v[36:37]
	v_pk_fma_f32 v[40:41], v[30:31], v[102:103], v[40:41]
	v_pk_fma_f32 v[36:37], v[114:115], v[66:67], v[36:37]
	v_pk_fma_f32 v[34:35], v[98:99], v[34:35], v[40:41]
	v_exp_f32_e32 v38, v36
	v_exp_f32_e32 v39, v37
	s_nop 0
	v_pk_add_f32 v[38:39], v[38:39], 1.0 op_sel_hi:[1,0]
	v_rcp_f32_e32 v38, v38
	v_rcp_f32_e32 v39, v39
	s_nop 0
	v_pk_mul_f32 v[36:37], v[36:37], v[38:39]
	s_nop 0
	v_pk_mul_f32 v[34:35], v[34:35], v[36:37]
	s_nop 0
	v_cvt_pk_bf16_f32 v157, v34, v35
	v_pk_fma_f32 v[34:35], v[0:1], v[120:121], v[124:125]
	global_store_dwordx4 v[128:129], v[154:157], off
	v_pk_fma_f32 v[34:35], v[4:5], v[116:117], v[34:35]
	v_pk_fma_f32 v[0:1], v[0:1], v[116:117], v[8:9]
	v_pk_fma_f32 v[24:25], v[24:25], v[112:113], v[34:35]
	v_pk_fma_f32 v[0:1], v[4:5], v[112:113], v[0:1]
	v_exp_f32_e32 v32, v24
	v_exp_f32_e32 v33, v25
	v_exp_f32_e32 v8, v0
	v_pk_add_f32 v[32:33], v[32:33], 1.0 op_sel_hi:[1,0]
	v_rcp_f32_e32 v32, v32
	v_rcp_f32_e32 v33, v33
	v_pk_fma_f32 v[34:35], v[12:13], v[104:105], v[108:109]
	v_pk_fma_f32 v[4:5], v[10:11], v[122:123], v[126:127]
	v_pk_fma_f32 v[34:35], v[16:17], v[100:101], v[34:35]
	v_pk_mul_f32 v[24:25], v[24:25], v[32:33]
	v_pk_fma_f32 v[28:29], v[28:29], v[96:97], v[34:35]
	v_pk_mul_f32 v[24:25], v[28:29], v[24:25]
	v_pk_fma_f32 v[28:29], v[2:3], v[122:123], v[126:127]
	v_pk_fma_f32 v[2:3], v[2:3], v[118:119], v[4:5]
	v_pk_fma_f32 v[28:29], v[6:7], v[118:119], v[28:29]
	v_pk_fma_f32 v[2:3], v[6:7], v[114:115], v[2:3]
	v_pk_fma_f32 v[26:27], v[26:27], v[114:115], v[28:29]
	v_exp_f32_e32 v28, v26
	v_exp_f32_e32 v29, v27
	v_exp_f32_e32 v9, v1
	v_exp_f32_e32 v4, v2
	v_exp_f32_e32 v5, v3
	v_cvt_pk_bf16_f32 v200, v24, v25
	v_pk_add_f32 v[28:29], v[28:29], 1.0 op_sel_hi:[1,0]
	v_pk_add_f32 v[8:9], v[8:9], 1.0 op_sel_hi:[1,0]
	v_pk_add_f32 v[4:5], v[4:5], 1.0 op_sel_hi:[1,0]
	v_rcp_f32_e32 v28, v28
	v_rcp_f32_e32 v29, v29
	v_rcp_f32_e32 v8, v8
	v_rcp_f32_e32 v9, v9
	v_rcp_f32_e32 v4, v4
	v_rcp_f32_e32 v5, v5
	v_pk_fma_f32 v[32:33], v[14:15], v[106:107], v[110:111]
	v_pk_fma_f32 v[10:11], v[22:23], v[106:107], v[110:111]
	v_pk_fma_f32 v[32:33], v[18:19], v[102:103], v[32:33]
	v_pk_fma_f32 v[12:13], v[12:13], v[100:101], v[20:21]
	v_pk_fma_f32 v[6:7], v[14:15], v[102:103], v[10:11]
	v_pk_fma_f32 v[30:31], v[30:31], v[98:99], v[32:33]
	v_pk_mul_f32 v[26:27], v[26:27], v[28:29]
	v_pk_fma_f32 v[12:13], v[16:17], v[96:97], v[12:13]
	v_pk_mul_f32 v[0:1], v[0:1], v[8:9]
	v_pk_fma_f32 v[6:7], v[18:19], v[98:99], v[6:7]
	v_pk_mul_f32 v[2:3], v[2:3], v[4:5]
	v_pk_mul_f32 v[26:27], v[30:31], v[26:27]
	v_pk_mul_f32 v[0:1], v[12:13], v[0:1]
	v_pk_mul_f32 v[2:3], v[6:7], v[2:3]
	v_cvt_pk_bf16_f32 v201, v26, v27
	v_cvt_pk_bf16_f32 v150, v0, v1
	v_cvt_pk_bf16_f32 v151, v2, v3
	global_store_dwordx4 v[88:89], v[198:201], off
	global_store_dwordx4 v[82:83], v[148:151], off
	s_barrier
	s_cbranch_vccnz .LBB0_1374

; __device__ __forceinline__ float sigmoidf_(float x) { return __builtin_amdgcn_rcpf(1.0f + __expf(-x)); }
;     __device__ __forceinline__ void operator()(AccRef acc, const Unit& u, int wr, int wc, int fr, int fq) const {
;     ...
;                 float o[4][4];
; #pragma unroll
;                 for (int j = 0; j < 4; ++j) {
;                     const float v0 = acc[ai][0][0][n][j], v1 = acc[ai][0][1][n][j], v2 = acc[ai][0][2][n][j], v3 = acc[ai][0][3][n][j];
;                     const float g0 = acc[ai][1][0][n][j], g1 = acc[ai][1][1][n][j], g2 = acc[ai][1][2][n][j], g3 = acc[ai][1][3][n][j];
;                     const float pv3 = dpp_upd<0x111>(h3v[j], v3), pv2 = dpp_upd<0x111>(h2v[j], v2), pg3 = dpp_upd<0x111>(h3g[j], g3), pg2 = dpp_upd<0x111>(h2g[j], g2);
;                     const float hv0 = bvv[j] + w2v[j] * v0 + w1v[j] * pv3 + w0v[j] * pv2, hv1 = bvv[j] + w2v[j] * v1 + w1v[j] * v0 + w0v[j] * pv3;
;                     const float hv2 = bvv[j] + w2v[j] * v2 + w1v[j] * v1 + w0v[j] * v0, hv3 = bvv[j] + w2v[j] * v3 + w1v[j] * v2 + w0v[j] * v1;
;                     const float hg0 = bvg[j] + w2g[j] * g0 + w1g[j] * pg3 + w0g[j] * pg2, hg1 = bvg[j] + w2g[j] * g1 + w1g[j] * g0 + w0g[j] * pg3;
;                     const float hg2 = bvg[j] + w2g[j] * g2 + w1g[j] * g1 + w0g[j] * g0, hg3 = bvg[j] + w2g[j] * g3 + w1g[j] * g2 + w0g[j] * g1;
;                     o[0][j] = hg0 * sigmoidf_(hg0) * hv0; o[1][j] = hg1 * sigmoidf_(hg1) * hv1; o[2][j] = hg2 * sigmoidf_(hg2) * hv2; o[3][j] = hg3 * sigmoidf_(hg3) * hv3; }
; #pragma unroll
;                 for (int m = 0; m < 4; ++m) { u32x2 w; w.x = cvt_pk_bf16(o[m][0], o[m][1]); w.y = cvt_pk_bf16(o[m][2], o[m][3]);
;                     *(u32x2*)(Aout + (size_t)(row0 + ai * 128 + m) * FH + hc0 + 4 * n) = w; } } }
.LBB0_1936:
	s_or_b64 exec, exec, s[34:35]
	s_waitcnt lgkmcnt(0)
	v_mov_b32_dpp v64, v8 row_shr:1 row_mask:0xf bank_mask:0xf
	v_mov_b32_dpp v65, v9 row_shr:1 row_mask:0xf bank_mask:0xf
	v_pk_fma_f32 v[44:45], v[24:25], v[120:121], v[124:125]
	v_mov_b32_dpp v40, v0 row_shr:1 row_mask:0xf bank_mask:0xf
	v_mov_b32_dpp v41, v1 row_shr:1 row_mask:0xf bank_mask:0xf
	v_pk_fma_f32 v[44:45], v[116:117], v[64:65], v[44:45]
	v_mov_b32_dpp v32, v20 row_shr:1 row_mask:0xf bank_mask:0xf
	v_pk_fma_f32 v[40:41], v[112:113], v[40:41], v[44:45]
	v_mov_b32_dpp v33, v21 row_shr:1 row_mask:0xf bank_mask:0xf
	v_exp_f32_e32 v44, v40
	v_exp_f32_e32 v45, v41
	v_pk_fma_f32 v[46:47], v[28:29], v[104:105], v[108:109]
	v_mov_b32_dpp v36, v12 row_shr:1 row_mask:0xf bank_mask:0xf
	v_pk_add_f32 v[44:45], v[44:45], 1.0 op_sel_hi:[1,0]
	v_rcp_f32_e32 v44, v44
	v_rcp_f32_e32 v45, v45
	v_mov_b32_dpp v37, v13 row_shr:1 row_mask:0xf bank_mask:0xf
	v_pk_fma_f32 v[46:47], v[100:101], v[32:33], v[46:47]
	v_mov_b32_dpp v66, v10 row_shr:1 row_mask:0xf bank_mask:0xf
	v_pk_fma_f32 v[36:37], v[96:97], v[36:37], v[46:47]
	v_pk_mul_f32 v[40:41], v[40:41], v[44:45]
	v_mov_b32_dpp v67, v11 row_shr:1 row_mask:0xf bank_mask:0xf
	v_pk_mul_f32 v[36:37], v[36:37], v[40:41]
	v_pk_fma_f32 v[40:41], v[26:27], v[122:123], v[126:127]
	v_mov_b32_dpp v42, v2 row_shr:1 row_mask:0xf bank_mask:0xf
	v_mov_b32_dpp v43, v3 row_shr:1 row_mask:0xf bank_mask:0xf
	v_pk_fma_f32 v[40:41], v[118:119], v[66:67], v[40:41]
	v_cvt_pk_bf16_f32 v146, v36, v37
	v_pk_fma_f32 v[40:41], v[114:115], v[42:43], v[40:41]
	v_mov_b32_dpp v34, v22 row_shr:1 row_mask:0xf bank_mask:0xf
	v_exp_f32_e32 v42, v40
	v_exp_f32_e32 v43, v41
	v_mov_b32_dpp v35, v23 row_shr:1 row_mask:0xf bank_mask:0xf
	v_pk_add_f32 v[42:43], v[42:43], 1.0 op_sel_hi:[1,0]
	v_rcp_f32_e32 v42, v42
	v_rcp_f32_e32 v43, v43
	v_pk_fma_f32 v[44:45], v[30:31], v[106:107], v[110:111]
	v_mov_b32_dpp v38, v14 row_shr:1 row_mask:0xf bank_mask:0xf
	v_mov_b32_dpp v39, v15 row_shr:1 row_mask:0xf bank_mask:0xf
	v_pk_fma_f32 v[44:45], v[102:103], v[34:35], v[44:45]
	v_pk_mul_f32 v[40:41], v[40:41], v[42:43]
	v_pk_fma_f32 v[38:39], v[98:99], v[38:39], v[44:45]
	v_pk_fma_f32 v[8:9], v[8:9], v[120:121], v[124:125]
	v_pk_mul_f32 v[38:39], v[38:39], v[40:41]
	v_pk_fma_f32 v[20:21], v[20:21], v[104:105], v[108:109]
	v_cvt_pk_bf16_f32 v147, v38, v39
	v_pk_fma_f32 v[38:39], v[4:5], v[120:121], v[124:125]
	global_store_dwordx4 v[132:133], v[144:147], off
	v_pk_fma_f32 v[38:39], v[24:25], v[116:117], v[38:39]
	s_and_b64 vcc, exec, s[10:11]
	v_pk_fma_f32 v[38:39], v[112:113], v[64:65], v[38:39]
	s_mov_b32 s35, s24
	v_exp_f32_e32 v36, v38
	v_exp_f32_e32 v37, v39
	s_mov_b32 s34, s26
	s_mov_b64 s[38:39], s[30:31]
	v_pk_add_f32 v[36:37], v[36:37], 1.0 op_sel_hi:[1,0]
	v_rcp_f32_e32 v36, v36
	v_rcp_f32_e32 v37, v37
	v_pk_fma_f32 v[40:41], v[16:17], v[104:105], v[108:109]
	s_mov_b64 s[36:37], s[28:29]
	v_pk_fma_f32 v[40:41], v[28:29], v[100:101], v[40:41]
	v_pk_mul_f32 v[36:37], v[38:39], v[36:37]
	v_pk_fma_f32 v[32:33], v[96:97], v[32:33], v[40:41]
	v_pk_fma_f32 v[40:41], v[18:19], v[106:107], v[110:111]
	v_pk_mul_f32 v[32:33], v[32:33], v[36:37]
	v_pk_fma_f32 v[36:37], v[6:7], v[122:123], v[126:127]
	v_cvt_pk_bf16_f32 v156, v32, v33
	v_pk_fma_f32 v[36:37], v[26:27], v[118:119], v[36:37]
	v_pk_fma_f32 v[40:41], v[30:31], v[102:103], v[40:41]
	v_pk_fma_f32 v[36:37], v[114:115], v[66:67], v[36:37]
	v_pk_fma_f32 v[34:35], v[98:99], v[34:35], v[40:41]
	v_exp_f32_e32 v38, v36
	v_exp_f32_e32 v39, v37
	s_nop 0
	v_pk_add_f32 v[38:39], v[38:39], 1.0 op_sel_hi:[1,0]
	v_rcp_f32_e32 v38, v38
	v_rcp_f32_e32 v39, v39
	s_nop 0
	v_pk_mul_f32 v[36:37], v[36:37], v[38:39]
	s_nop 0
	v_pk_mul_f32 v[34:35], v[34:35], v[36:37]
	s_nop 0
	v_cvt_pk_bf16_f32 v157, v34, v35
	v_pk_fma_f32 v[34:35], v[0:1], v[120:121], v[124:125]
	global_store_dwordx4 v[128:129], v[154:157], off
	v_pk_fma_f32 v[34:35], v[4:5], v[116:117], v[34:35]
	v_pk_fma_f32 v[0:1], v[0:1], v[116:117], v[8:9]
	v_pk_fma_f32 v[24:25], v[24:25], v[112:113], v[34:35]
	v_pk_fma_f32 v[0:1], v[4:5], v[112:113], v[0:1]
	v_exp_f32_e32 v32, v24
	v_exp_f32_e32 v33, v25
	v_exp_f32_e32 v8, v0
	v_pk_add_f32 v[32:33], v[32:33], 1.0 op_sel_hi:[1,0]
	v_rcp_f32_e32 v32, v32
	v_rcp_f32_e32 v33, v33
	v_pk_fma_f32 v[34:35], v[12:13], v[104:105], v[108:109]
	v_pk_fma_f32 v[4:5], v[10:11], v[122:123], v[126:127]
	v_pk_fma_f32 v[34:35], v[16:17], v[100:101], v[34:35]
	v_pk_mul_f32 v[24:25], v[24:25], v[32:33]
	v_pk_fma_f32 v[28:29], v[28:29], v[96:97], v[34:35]
	v_pk_mul_f32 v[24:25], v[28:29], v[24:25]
	v_pk_fma_f32 v[28:29], v[2:3], v[122:123], v[126:127]
	v_pk_fma_f32 v[2:3], v[2:3], v[118:119], v[4:5]
	v_pk_fma_f32 v[28:29], v[6:7], v[118:119], v[28:29]
	v_pk_fma_f32 v[2:3], v[6:7], v[114:115], v[2:3]
	v_pk_fma_f32 v[26:27], v[26:27], v[114:115], v[28:29]
	v_exp_f32_e32 v28, v26
	v_exp_f32_e32 v29, v27
	v_exp_f32_e32 v9, v1
	v_exp_f32_e32 v4, v2
	v_exp_f32_e32 v5, v3
	v_cvt_pk_bf16_f32 v200, v24, v25
	v_pk_add_f32 v[28:29], v[28:29], 1.0 op_sel_hi:[1,0]
	v_pk_add_f32 v[8:9], v[8:9], 1.0 op_sel_hi:[1,0]
	v_pk_add_f32 v[4:5], v[4:5], 1.0 op_sel_hi:[1,0]
	v_rcp_f32_e32 v28, v28
	v_rcp_f32_e32 v29, v29
	v_rcp_f32_e32 v8, v8
	v_rcp_f32_e32 v9, v9
	v_rcp_f32_e32 v4, v4
	v_rcp_f32_e32 v5, v5
	v_pk_fma_f32 v[32:33], v[14:15], v[106:107], v[110:111]
	v_pk_fma_f32 v[10:11], v[22:23], v[106:107], v[110:111]
	v_pk_fma_f32 v[32:33], v[18:19], v[102:103], v[32:33]
	v_pk_fma_f32 v[12:13], v[12:13], v[100:101], v[20:21]
	v_pk_fma_f32 v[6:7], v[14:15], v[102:103], v[10:11]
	v_pk_fma_f32 v[30:31], v[30:31], v[98:99], v[32:33]
	v_pk_mul_f32 v[26:27], v[26:27], v[28:29]
	v_pk_fma_f32 v[12:13], v[16:17], v[96:97], v[12:13]
	v_pk_mul_f32 v[0:1], v[0:1], v[8:9]
	v_pk_fma_f32 v[6:7], v[18:19], v[98:99], v[6:7]
	v_pk_mul_f32 v[2:3], v[2:3], v[4:5]
	v_pk_mul_f32 v[26:27], v[30:31], v[26:27]
	v_pk_mul_f32 v[0:1], v[12:13], v[0:1]
	v_pk_mul_f32 v[2:3], v[6:7], v[2:3]
	v_cvt_pk_bf16_f32 v201, v26, v27
	v_cvt_pk_bf16_f32 v150, v0, v1
	v_cvt_pk_bf16_f32 v151, v2, v3
	global_store_dwordx4 v[88:89], v[198:201], off
	global_store_dwordx4 v[82:83], v[148:151], off
	s_barrier
	s_cbranch_vccnz .LBB0_1955
